# same-layer windows, scan-shadow window 4 iterations (A=2,P=4,B=2)
# speedup vs baseline: 1.0013x; 1.0013x over previous
; #define LAS __attribute__((address_space(3)))
; __device__ __forceinline__ void convert_layer_static(const PT& a, LAS unsigned char* lds, int l, int gw, int NGW, int wave, int lane, int r_end = IT_LAYER) {
;     for (int r = 2 * gw; r < r_end; r += 2 * NGW) cv_pair(a, lds, l, r, wave, lane);
; }
; __device__ __forceinline__ void prologue_a(const PT& a, LAS unsigned char* lds) {
;     ...
;     convert_layer_static(a, lds, 0, gw, NGW, wave, lane);
;     for (int cl_ = 1; cl_ < DEPTH; ++cl_) convert_layer_static(a, lds, cl_, gw, NGW, wave, lane, CV_PRO_ITEMS);
.LBB0_22:
	s_or_saveexec_b64 s[12:13], s[0:1]
	v_lshlrev_b32_e32 v109, 1, v66
	v_readlane_b32 s0, v252, 4
	v_mul_lo_u32 v3, v12, s6
	s_lshl_b32 s17, s0, 4
	v_add_u32_e32 v115, 0, v3
	v_lshlrev_b32_e32 v111, 5, v109
	v_readlane_b32 s1, v252, 5
	s_xor_b64 exec, exec, s[12:13]
	s_cbranch_execz .LBB0_110
	v_and_b32_e32 v74, 28, v68
	v_and_b32_e32 v76, 56, v2
	v_mov_b32_e32 v79, 0
	v_lshl_add_u32 v3, v74, 2, v115
	v_mul_u32_u24_e32 v121, 0x84, v67
	v_mul_u32_u24_e32 v113, 0x84, v76
	v_lshlrev_b32_e32 v2, 2, v67
	v_mov_b32_e32 v75, v79
	v_or_b32_e32 v69, 8, v67
	v_or_b32_e32 v97, 16, v67
	v_or_b32_e32 v99, 24, v67
	v_or_b32_e32 v101, 32, v67
	v_or_b32_e32 v103, 40, v67
	v_or_b32_e32 v105, 48, v67
	v_or_b32_e32 v107, 56, v67
	v_mov_b32_e32 v77, v79
	v_add3_u32 v117, v115, v113, v2
	v_lshlrev_b32_e32 v119, 5, v109
	s_lshl_b32 s36, s17, 5
	s_mov_b64 s[18:19], 0
	s_movk_i32 s37, 0x393f
	s_movk_i32 s38, 0x453f
	s_movk_i32 s39, 0x4d3f
	s_movk_i32 s40, 0x793f
	s_movk_i32 s41, 0x15ff
	s_movk_i32 s42, 0xba3
	s_movk_i32 s43, 0x1600
	s_movk_i32 s44, 0x3ff
	s_mov_b64 s[20:21], 0xea00000
	s_mov_b32 s45, 0x478bbced
	s_movk_i32 s46, 0x9f
	s_movk_i32 s47, 0x109
	v_lshlrev_b32_e32 v78, 2, v74
	v_add_u32_e32 v123, v3, v121
	v_lshlrev_b32_e32 v80, 1, v76
	s_mov_b32 s48, 0x573f
	v_readlane_b32 s100, v252, 4
	s_cmp_eq_u32 s100, 0x100
	s_cselect_b32 s48, s48, 0x8f3f
	v_mov_b32_e32 v127, 0xea00
	v_mov_b32_e32 v129, 5
	v_mov_b32_e32 v130, 0x23a40
	v_mov_b32_e32 v131, 0x23a38
	v_mov_b32_e32 v132, 6
	v_mov_b32_e32 v133, 0x80
	v_mov_b32_e32 v134, 0x23a20
	v_mov_b32_e32 v135, 0x23a18
	v_mov_b32_e32 v136, 0x23a10
	v_mov_b32_e32 v137, v109
	s_branch .LBB0_25

; __device__ __forceinline__ int opaque_tid() { int t = threadIdx.x; asm volatile("" : "+v"(t)); return t; }
;     for (int it = 0; it < budget; ++it) {
;         unsigned r = 0; if (lane == 0) r = __hip_atomic_fetch_add(ctr, 2u, __ATOMIC_RELAXED, __HIP_MEMORY_SCOPE_AGENT);
;         r = (unsigned)__builtin_amdgcn_readfirstlane((int)r) + (unsigned)CV_PRO_ITEMS;
;         if (r >= (unsigned)IT_LAYER) break;
;         cv_pair(a, lds, l, (int)r, wave, lane);
;     }
; }
; __global__ void __launch_bounds__(NTHREADS, 2) mk_fwd(Args args) {
;     ...
;             if (l + 1 < DEPTH && !(G >= 256 && bid < 128)) { __syncthreads(); const int tid_ = opaque_tid(); convert_layer_queue(pt, lds, l + 1, cvq, tid_ >> 6, tid_ & 63); }
.LBB0_1377:
	s_cmp_eq_u32 s64, 0x63
	v_readlane_b32 s2, v253, 61
	s_cselect_b64 s[0:1], -1, 0
	v_readlane_b32 s3, v253, 62
	s_or_b64 s[0:1], s[2:3], s[0:1]
	v_readlane_b32 s2, v252, 4
	s_cmp_lg_u32 s2, 0x100
	s_cselect_b64 s[2:3], -1, 0
	s_or_b64 s[0:1], s[0:1], s[2:3]
	v_readlane_b32 s28, v254, 55
	s_mov_b32 s36, s64
	s_and_b64 vcc, exec, s[0:1]
	v_readlane_b32 s29, v254, 56
	s_cbranch_vccnz .LBB0_1470
	v_readlane_b32 s0, v254, 53
	v_readlane_b32 s1, v254, 54
	s_mov_b32 s3, s1
	s_lshl_b32 s2, s36, 6
	s_lshl_b64 s[0:1], s[2:3], 2
	v_readlane_b32 s4, v254, 60
	v_readlane_b32 s5, v254, 61
	s_add_u32 s0, s4, s0
	s_addc_u32 s1, s5, s1
	s_add_u32 s0, s0, 0x8000
	s_addc_u32 s1, s1, 0
	s_add_i32 s2, s36, 0
	s_mul_hi_u32 s33, s2, 0x2c00000
	s_mul_i32 s34, s2, 0x2c00000
	s_mul_hi_u32 s35, s2, 0x1600000
	s_mul_i32 s50, s2, 0x1600000
	s_lshl_b32 s6, s2, 11
	s_mov_b32 s7, s3
	s_lshl_b64 s[8:9], s[2:3], 24
	s_lshl_b64 s[10:11], s[2:3], 23
	s_mul_hi_u32 s51, s2, 0xc00000
	s_mul_i32 s52, s2, 0xc00000
	s_mul_hi_u32 s53, s2, 0x7280000
	s_mul_i32 s54, s2, 0x7280000
	s_mul_hi_u32 s55, s2, 0x3a00000
	v_writelane_b32 v254, s2, 53
	v_mov_b32_e32 v2, v0
	s_mul_i32 s56, s2, 0x3a00000
	v_writelane_b32 v254, s3, 54
	s_waitcnt vmcnt(0) lgkmcnt(0)
	s_barrier
	s_movk_i32 s2, 0x4200
	v_lshrrev_b32_e32 v1, 6, v2
	v_and_b32_e32 v3, 63, v2
	v_readfirstlane_b32 s100, v1
	v_readlane_b32 s101, v252, 0
	s_sub_u32 s101, s101, 128
	s_lshl_b32 s101, s101, 3
	s_add_u32 s100, s100, s101
	s_lshl_b32 s100, s100, 1
	s_add_u32 s100, s100, 0x2800
	v_mul_lo_u32 v1, v1, s2
	v_cmp_eq_u32_e64 s[40:41], 0, v3
	v_add_u32_e32 v3, 0, v1
	v_lshlrev_b32_e32 v1, 2, v2
	v_and_b32_e32 v66, 28, v1
	v_bfe_u32 v1, v2, 3, 3
	v_lshlrev_b32_e32 v2, 3, v2
	v_and_b32_e32 v68, 56, v2
	v_lshl_add_u32 v4, v66, 2, v3
	v_mul_u32_u24_e32 v5, 0x84, v1
	v_mul_u32_u24_e32 v2, 0x84, v68
	v_lshlrev_b32_e32 v6, 2, v1
	v_or_b32_e32 v67, 8, v1
	v_or_b32_e32 v69, 16, v1
	v_or_b32_e32 v71, 24, v1
	v_or_b32_e32 v73, 32, v1
	v_or_b32_e32 v75, 40, v1
	v_or_b32_e32 v77, 48, v1
	v_or_b32_e32 v79, 56, v1
	v_add3_u32 v81, v3, v2, v6
	s_mov_b32 s57, 0x4
	v_add_u32_e32 v83, v4, v5
	s_branch .LBB0_1381
